# P0 weight copies rewritten by hand: 16-byte loads, register transpose (no LDS), whole 8 KiB item in flight per wave (on top of v54)
# baseline (speedup 1.0000x reference)
; #define LAS __attribute__((address_space(3)))
; __global__ void __launch_bounds__(512) fwd_mega(Args a) {
;     ...
;     const int tid = threadIdx.x, lane = tid & 63, wave = __builtin_amdgcn_readfirstlane(tid >> 6);
;     const int G = gridDim.x, bx = blockIdx.x;
;     const int vcu = (G % 8 == 0) ? (bx % 8) * (G / 8) + bx / 8 : bx;
;     unsigned char* ws = a.ws;
;     bf16 *Win_t = (bf16*)(ws + WS_WIN), *Wq_t = (bf16*)(ws + WS_WQ), *Wkv_t = (bf16*)(ws + WS_WKV), *WoA_t = (bf16*)(ws + WS_WOA), *WoB_t = (bf16*)(ws + WS_WOB),
;          *Wout_t = (bf16*)(ws + WS_WOUT), *Wup_t = (bf16*)(ws + WS_WUP), *Wdn_t = (bf16*)(ws + WS_WDN);
;     float* rope = (float*)(ws + WS_ROPE);
;     float *ssqQ = (float*)(ws + WS_SSQQ), *ssqKV = (float*)(ws + WS_SSQKV), *ssqY = (float*)(ws + WS_SSQY), *ssqY2 = (float*)(ws + WS_SSQY2);
;     bf16 *XN = (bf16*)(ws + WS_XN), *CQ = (bf16*)(ws + WS_CQ), *CKV = (bf16*)(ws + WS_CKV), *KR = (bf16*)(ws + WS_KR), *KS = (bf16*)(ws + WS_KS), *VS = (bf16*)(ws + WS_VS), *QS = (bf16*)(ws + WS_QS);
;     bf16 *QN = (bf16*)(ws + WS_QN), *QR = (bf16*)(ws + WS_QR), *KN = (bf16*)(ws + WS_KN), *VV = (bf16*)(ws + WS_V), *MG = (bf16*)(ws + WS_MG), *GG = (bf16*)(ws + WS_G);
;     bf16 *GT = (bf16*)(ws + WS_GT), *Y = (bf16*)(ws + WS_Y), *Y2 = (bf16*)(ws + WS_Y2), *H2 = (bf16*)(ws + WS_H2);
;     float *X1 = (float*)(ws + WS_X1), *AH = (float*)(ws + WS_AH), *BH = (float*)(ws + WS_BH);
;     const int gw = vcu * 8 + wave, NGW = G * 8;
;     const int lo = a.ph_lo, hi = a.ph_hi;
;     ...
;     if (IN(0)) {
;         LAS float* scr = (LAS float*)(lds + wave * 16384);
;         constexpr int I_IN = 32 * 234, I_Q = 8 * 96, I_KV = 4 * 128, I_O = 32 * 64, I_UP = 32 * 352, I_DN = 88 * 64;
;         constexpr int NITEMS = I_IN + I_Q + I_KV + 3 * I_O + I_UP + I_DN;
;         for (int it = gw; it < NITEMS; it += NGW) {
;             int r = it;
;             if (r < I_IN) { const int kb = r / 234, c = (r % 234) * 32; int d0, ds = 1;
;                 if (c < 768) d0 = c; else if (c < 832) { d0 = 768 + (c - 768) / 32; ds = 2; } else d0 = c + 192;
;                 tr_item(a.w_in, 2048, 7488, kb * 64, c, Win_t, d0, ds, nullptr, scr, lane); continue; } r -= I_IN;
;             if (r < I_Q) { const int kb = r / 96, c = (r % 96) * 32, h = c / 192, w = c % 192; int d0, ds = 1;
;                 if (w < 128) d0 = 128 * h + w; else { d0 = 2048 + 64 * h + (w - 128) / 32; ds = 2; }
.LBB0_2:
	s_load_dwordx16 s[4:19], s[0:1], 0x40
	s_lshr_b32 s0, s61, 6
	v_and_b32_e32 v206, 63, v162
	s_waitcnt lgkmcnt(0)
	v_writelane_b32 v253, s4, 0
	s_nop 1
	v_writelane_b32 v253, s5, 1
	v_writelane_b32 v253, s6, 2
	v_writelane_b32 v253, s7, 3
	v_writelane_b32 v253, s8, 4
	v_writelane_b32 v253, s9, 5
	v_writelane_b32 v253, s10, 6
	v_writelane_b32 v253, s11, 7
	v_writelane_b32 v253, s12, 8
	v_writelane_b32 v253, s13, 9
	v_writelane_b32 v253, s14, 10
	v_writelane_b32 v253, s15, 11
	v_writelane_b32 v253, s16, 12
	v_writelane_b32 v253, s17, 13
	v_writelane_b32 v253, s18, 14
	v_writelane_b32 v253, s19, 15
	s_add_u32 s6, s52, 0x100000
	s_addc_u32 s7, s53, 0
	s_add_u32 s66, s52, 0x1f00000
	s_addc_u32 s67, s53, 0
	s_add_u32 s64, s52, 0x2200000
	s_addc_u32 s65, s53, 0
	s_add_u32 s1, s52, 0x2400000
	v_writelane_b32 v253, s1, 16
	s_addc_u32 s1, s53, 0
	v_writelane_b32 v253, s1, 17
	s_add_u32 s1, s52, 0x2c00000
	v_writelane_b32 v253, s1, 18
	s_addc_u32 s1, s53, 0
	v_writelane_b32 v253, s1, 19
	s_add_u32 s1, s52, 0x3400000
	v_writelane_b32 v253, s1, 20
	s_addc_u32 s1, s53, 0
	s_add_u32 s4, s52, 0x3c00000
	v_writelane_b32 v253, s1, 21
	s_addc_u32 s5, s53, 0
	v_writelane_b32 v253, s4, 22
	s_nop 1
	v_writelane_b32 v253, s5, 23
	s_add_u32 s4, s52, 0x6800000
	s_addc_u32 s5, s53, 0
	v_writelane_b32 v253, s4, 24
	s_add_u32 s68, s52, 0x7e00000
	s_addc_u32 s69, s53, 0
	v_writelane_b32 v253, s5, 25
	v_writelane_b32 v253, s72, 26
	s_lshl_b32 s1, s2, 3
	s_add_i32 s34, s1, s0
	v_writelane_b32 v253, s73, 27
	v_writelane_b32 v253, s74, 28
	v_writelane_b32 v253, s75, 29
	v_writelane_b32 v253, s76, 30
	v_writelane_b32 v253, s77, 31
	v_writelane_b32 v253, s78, 32
	v_writelane_b32 v253, s79, 33
	v_writelane_b32 v253, s80, 34
	s_lshl_b32 s56, s3, 3
	v_writelane_b32 v253, s81, 35
	s_cmp_lt_i32 s54, 1
	v_writelane_b32 v253, s82, 36
	s_cselect_b64 s[4:5], -1, 0
	s_cmp_gt_i32 s55, 0
	v_writelane_b32 v253, s83, 37
	s_cselect_b64 s[8:9], -1, 0
	v_writelane_b32 v253, s84, 38
	s_and_b64 s[4:5], s[4:5], s[8:9]
	v_writelane_b32 v253, s85, 39
	s_andn2_b64 vcc, exec, s[4:5]
	v_writelane_b32 v253, s86, 40
	v_writelane_b32 v253, s87, 41
	s_cbranch_vccnz .LBB0_92
	s_cmpk_gt_i32 s34, 0x7c3f
	s_cbranch_scc1 .LBB0_83
	v_and_b32_e32 v1, 7, v206
	v_lshlrev_b32_e32 v1, 4, v1
	v_lshrrev_b32_e32 v2, 3, v206
	v_lshlrev_b32_e32 v5, 5, v2
	s_mov_b32 s33, s34
.Lp0_item:
	s_mov_b32 s35, s33
	s_mov_b32 s71, 0
	s_mov_b32 s39, 1
.Lp0_in:
	s_cmp_lt_u32 s35, 7488
	s_cbranch_scc1 .Lp0_in_do
	s_sub_u32 s35, s35, 7488
	s_branch .Lp0_q
.Lp0_in_do:
	s_mul_i32 s36, s35, 8963
	s_lshr_b32 s36, s36, 21
	s_mul_i32 s42, s36, 234
	s_sub_u32 s37, s35, s42
	s_lshl_b32 s38, s37, 5
	s_mov_b32 s44, s38
	s_cmp_lt_u32 s37, 24
	s_cbranch_scc1 .Lp0_in_d
	s_cmp_lt_u32 s37, 26
	s_cbranch_scc0 .Lp0_in_hi
	s_add_u32 s38, s37, 744
	s_mov_b32 s39, 2
	s_branch .Lp0_in_d
.Lp0_in_hi:
	s_add_u32 s38, s38, 192
.Lp0_in_d:
	v_readlane_b32 s8, v253, 36
	v_readlane_b32 s9, v253, 37
	s_add_u32 s10, s52, 0x100000
	s_addc_u32 s11, s53, 0
	s_movk_i32 s40, 0x800
	s_mov_b32 s41, 7488
	s_branch .Lp0_go
.Lp0_q:
	s_cmp_lt_u32 s35, 768
	s_cbranch_scc1 .Lp0_q_do
	s_sub_u32 s35, s35, 768
	s_branch .Lp0_kv
.Lp0_q_do:
	s_mul_i32 s36, s35, 683
	s_lshr_b32 s36, s36, 16
	s_mul_i32 s42, s36, 96
	s_sub_u32 s37, s35, s42
	s_lshl_b32 s44, s37, 5
	s_mul_i32 s42, s37, 43
	s_lshr_b32 s42, s42, 8
	s_mul_i32 s43, s42, 6
	s_sub_u32 s43, s37, s43
	s_cmp_lt_u32 s43, 4
	s_cbranch_scc0 .Lp0_q_rope
	s_lshl_b32 s38, s42, 7
	s_lshl_b32 s43, s43, 5
	s_add_u32 s38, s38, s43
	s_branch .Lp0_q_d
.Lp0_q_rope:
	s_lshl_b32 s38, s42, 6
	s_add_u32 s38, s38, s43
	s_add_u32 s38, s38, 2044
	s_mov_b32 s39, 2
.Lp0_q_d:
	v_readlane_b32 s8, v253, 40
	v_readlane_b32 s9, v253, 41
	v_readlane_b32 s12, v253, 38
	v_readlane_b32 s13, v253, 39
	s_add_u32 s10, s52, 0x1f00000
	s_addc_u32 s11, s53, 0
	s_movk_i32 s40, 0x200
	s_movk_i32 s41, 0xc00
	s_mov_b32 s71, 1
	s_branch .Lp0_go
.Lp0_kv:
	s_cmp_lt_u32 s35, 512
	s_cbranch_scc1 .Lp0_kv_do
	s_sub_u32 s35, s35, 512
	s_branch .Lp0_o
.Lp0_kv_do:
	s_lshr_b32 s36, s35, 7
	s_and_b32 s37, s35, 127
	s_lshl_b32 s44, s37, 5
	s_lshr_b32 s42, s37, 3
	s_and_b32 s43, s37, 7
	s_lshl_b32 s43, s43, 5
	s_lshl_b32 s38, s42, 7
	s_add_u32 s38, s38, s43
	s_cmp_lt_u32 s43, 128
	s_cbranch_scc1 .Lp0_kv_d
	s_add_u32 s38, s38, 1920
.Lp0_kv_d:
	v_readlane_b32 s8, v253, 2
	v_readlane_b32 s9, v253, 3
	v_readlane_b32 s12, v253, 0
	v_readlane_b32 s13, v253, 1
	s_add_u32 s10, s52, 0x2200000
	s_addc_u32 s11, s53, 0
	s_movk_i32 s40, 0x100
	s_movk_i32 s41, 0x1000
	s_mov_b32 s71, 1
	s_branch .Lp0_go
.Lp0_o:
	s_cmp_lt_u32 s35, 6144
	s_cbranch_scc1 .Lp0_o_do
	s_sub_u32 s35, s35, 6144
	s_branch .Lp0_up
.Lp0_o_do:
	s_lshr_b32 s42, s35, 11
	s_and_b32 s43, s35, 2047
	s_lshr_b32 s36, s43, 6
	s_and_b32 s37, s43, 63
	s_lshl_b32 s38, s37, 5
	s_mov_b32 s44, s38
	s_cmp_eq_u32 s42, 0
	s_cbranch_scc0 .Lp0_o1
	v_readlane_b32 s8, v253, 8
	v_readlane_b32 s9, v253, 9
	s_add_u32 s10, s52, 0x2400000
	s_addc_u32 s11, s53, 0
	s_branch .Lp0_o_d
; #define LAS __attribute__((address_space(3)))
; __device__ __forceinline__ unsigned pk2(float lo, float hi) { return f2bf(lo) | (f2bf(hi) << 16); }
; __device__ __forceinline__ void tr_item(const float* W, int K, int Nsrc, int k0, int nsrc0, bf16* WT, int drow0, int dstride, const float* gain, LAS float* scr, int lane) {
; #pragma unroll 8
;     for (int i = 0; i < 32; ++i) { const int kk = 2 * i + (lane >> 5); float v = W[(size_t)(k0 + kk) * Nsrc + nsrc0 + (lane & 31)]; if (gain) v *= gain[k0 + kk]; scr[kk * 33 + (lane & 31)] = v; }
;     asm volatile("s_waitcnt lgkmcnt(0)" ::: "memory");
;     const int c = lane & 7;
; #pragma unroll
;     for (int j = 0; j < 4; ++j) { const int n = (lane >> 3) + 8 * j; const LAS float* s = scr + (8 * c) * 33 + n;
;         v4u o; o.x = pk2(s[0 * 33], s[1 * 33]); o.y = pk2(s[2 * 33], s[3 * 33]); o.z = pk2(s[4 * 33], s[5 * 33]); o.w = pk2(s[6 * 33], s[7 * 33]);
;         *(v4u*)(WT + (size_t)(drow0 + n * dstride) * K + k0 + 8 * c) = o; }
;     asm volatile("s_waitcnt lgkmcnt(0)" ::: "memory");
; }
; __global__ void __launch_bounds__(512) fwd_mega(Args a) {
;     ...
;             if (r < 3 * I_O) { const int wsel = r / I_O, q = r % I_O, kb = q / 64, c = (q % 64) * 32;
;                 tr_item(wsel == 0 ? a.w_o_mla : wsel == 1 ? a.w_o_swa : a.w_out, 2048, 2048, kb * 64, c, wsel == 0 ? WoA_t : wsel == 1 ? WoB_t : Wout_t, c, 1, nullptr, scr, lane); continue; } r -= 3 * I_O;
;             if (r < I_UP) { const int kb = r / 352, c = (r % 352) * 32; int d0;
;                 if (c < DFF) d0 = 256 * (c / 128) + (c % 128); else { const int c2 = c - DFF; d0 = 256 * (c2 / 128) + 128 + (c2 % 128); }
;                 tr_item(a.w_up, 2048, 11264, kb * 64, c, Wup_t, d0, 1, nullptr, scr, lane); continue; } r -= I_UP;
;             { const int kb = r / 64, c = (r % 64) * 32; tr_item(a.w_down, DFF, 2048, kb * 64, c, Wdn_t, c, 1, nullptr, scr, lane); }
.Lp0_o1:
	s_cmp_eq_u32 s42, 1
	s_cbranch_scc0 .Lp0_o2
	v_readlane_b32 s8, v253, 10
	v_readlane_b32 s9, v253, 11
	s_add_u32 s10, s52, 0x2c00000
	s_addc_u32 s11, s53, 0
	s_branch .Lp0_o_d
.Lp0_o2:
	v_readlane_b32 s8, v253, 12
	v_readlane_b32 s9, v253, 13
	s_add_u32 s10, s52, 0x3400000
	s_addc_u32 s11, s53, 0
.Lp0_o_d:
	s_movk_i32 s40, 0x800
	s_movk_i32 s41, 0x800
	s_branch .Lp0_go
.Lp0_up:
	s_cmp_lt_u32 s35, 11264
	s_cbranch_scc1 .Lp0_up_do
	s_sub_u32 s35, s35, 11264
	s_branch .Lp0_dn
.Lp0_up_do:
	s_mul_i32 s36, s35, 2979
	s_lshr_b32 s36, s36, 20
	s_mul_i32 s42, s36, 352
	s_sub_u32 s37, s35, s42
	s_lshl_b32 s44, s37, 5
	s_mov_b32 s43, 0
	s_cmp_lt_u32 s37, 176
	s_cbranch_scc1 .Lp0_up_a
	s_sub_u32 s37, s37, 176
	s_movk_i32 s43, 0x80
.Lp0_up_a:
	s_lshr_b32 s38, s37, 2
	s_lshl_b32 s38, s38, 8
	s_and_b32 s42, s37, 3
	s_lshl_b32 s42, s42, 5
	s_add_u32 s38, s38, s42
	s_add_u32 s38, s38, s43
	v_readlane_b32 s8, v253, 14
	v_readlane_b32 s9, v253, 15
	s_add_u32 s10, s52, 0x3c00000
	s_addc_u32 s11, s53, 0
	s_movk_i32 s40, 0x800
	s_movk_i32 s41, 0x2c00
	s_branch .Lp0_go
.Lp0_dn:
	s_lshr_b32 s36, s35, 6
	s_and_b32 s37, s35, 63
	s_lshl_b32 s38, s37, 5
	s_mov_b32 s44, s38
	s_mov_b64 s[8:9], s[28:29]
	s_add_u32 s10, s52, 0x6800000
	s_addc_u32 s11, s53, 0
	s_movk_i32 s40, 0x1600
	s_movk_i32 s41, 0x800
.Lp0_go:
	s_lshl_b32 s45, s41, 2
	s_lshl_b32 s42, s36, 6
	s_mul_i32 s43, s42, s41
	s_add_u32 s43, s43, s44
	s_mul_hi_u32 s37, s43, 4
	s_lshl_b32 s43, s43, 2
	s_add_u32 s46, s8, s43
	s_addc_u32 s47, s9, s37
	s_lshl_b32 s43, s45, 3
	v_mad_u32_u24 v3, v2, s43, v1
	s_mul_i32 s43, s38, s40
	s_add_u32 s43, s43, s42
	s_lshl_b32 s43, s43, 1
	s_add_u32 s48, s10, s43
	s_addc_u32 s49, s11, 0
	s_mul_i32 s70, s39, s40
	s_lshl_b32 s70, s70, 1
	s_lshr_b32 s43, s70, 2
	v_lshlrev_b32_e32 v6, 4, v2
	v_mad_u32_u24 v4, v1, s43, v6
	s_cmp_eq_u32 s71, 0
	s_cbranch_scc1 .Lp0_ld
	s_lshl_b32 s43, s42, 2
	s_add_u32 s50, s12, s43
	s_addc_u32 s51, s13, 0
	global_load_dwordx4 v[40:43], v5, s[50:51]
	global_load_dwordx4 v[44:47], v5, s[50:51] offset:16
.Lp0_ld:
	global_load_dwordx4 v[8:11], v3, s[46:47]
	s_add_u32 s46, s46, s45
	s_addc_u32 s47, s47, 0
	global_load_dwordx4 v[12:15], v3, s[46:47]
	s_add_u32 s46, s46, s45
	s_addc_u32 s47, s47, 0
	global_load_dwordx4 v[16:19], v3, s[46:47]
	s_add_u32 s46, s46, s45
	s_addc_u32 s47, s47, 0
	global_load_dwordx4 v[20:23], v3, s[46:47]
	s_add_u32 s46, s46, s45
	s_addc_u32 s47, s47, 0
	global_load_dwordx4 v[24:27], v3, s[46:47]
	s_add_u32 s46, s46, s45
	s_addc_u32 s47, s47, 0
	global_load_dwordx4 v[28:31], v3, s[46:47]
	s_add_u32 s46, s46, s45
	s_addc_u32 s47, s47, 0
	global_load_dwordx4 v[32:35], v3, s[46:47]
	s_add_u32 s46, s46, s45
	s_addc_u32 s47, s47, 0
	global_load_dwordx4 v[36:39], v3, s[46:47]
	s_waitcnt vmcnt(0)
	s_cmp_eq_u32 s71, 0
	s_cbranch_scc1 .Lp0_cv
	v_mul_f32_e32 v8, v8, v40
	v_mul_f32_e32 v9, v9, v40
	v_mul_f32_e32 v10, v10, v40
	v_mul_f32_e32 v11, v11, v40
	v_mul_f32_e32 v12, v12, v41
	v_mul_f32_e32 v13, v13, v41
	v_mul_f32_e32 v14, v14, v41
	v_mul_f32_e32 v15, v15, v41
	v_mul_f32_e32 v16, v16, v42
	v_mul_f32_e32 v17, v17, v42
	v_mul_f32_e32 v18, v18, v42
	v_mul_f32_e32 v19, v19, v42
	v_mul_f32_e32 v20, v20, v43
	v_mul_f32_e32 v21, v21, v43
	v_mul_f32_e32 v22, v22, v43
	v_mul_f32_e32 v23, v23, v43
	v_mul_f32_e32 v24, v24, v44
	v_mul_f32_e32 v25, v25, v44
	v_mul_f32_e32 v26, v26, v44
	v_mul_f32_e32 v27, v27, v44
	v_mul_f32_e32 v28, v28, v45
	v_mul_f32_e32 v29, v29, v45
	v_mul_f32_e32 v30, v30, v45
	v_mul_f32_e32 v31, v31, v45
	v_mul_f32_e32 v32, v32, v46
	v_mul_f32_e32 v33, v33, v46
	v_mul_f32_e32 v34, v34, v46
	v_mul_f32_e32 v35, v35, v46
	v_mul_f32_e32 v36, v36, v47
	v_mul_f32_e32 v37, v37, v47
	v_mul_f32_e32 v38, v38, v47
	v_mul_f32_e32 v39, v39, v47
.Lp0_cv:
	v_cvt_pk_bf16_f32 v48, v8, v12
	v_cvt_pk_bf16_f32 v49, v16, v20
	v_cvt_pk_bf16_f32 v50, v24, v28
	v_cvt_pk_bf16_f32 v51, v32, v36
	v_cvt_pk_bf16_f32 v52, v9, v13
	v_cvt_pk_bf16_f32 v53, v17, v21
	v_cvt_pk_bf16_f32 v54, v25, v29
	v_cvt_pk_bf16_f32 v55, v33, v37
	v_cvt_pk_bf16_f32 v56, v10, v14
	v_cvt_pk_bf16_f32 v57, v18, v22
	v_cvt_pk_bf16_f32 v58, v26, v30
	v_cvt_pk_bf16_f32 v59, v34, v38
	v_cvt_pk_bf16_f32 v60, v11, v15
	v_cvt_pk_bf16_f32 v61, v19, v23
	v_cvt_pk_bf16_f32 v62, v27, v31
	v_cvt_pk_bf16_f32 v63, v35, v39
	global_store_dwordx4 v4, v[48:51], s[48:49]
	s_add_u32 s48, s48, s70
	s_addc_u32 s49, s49, 0
	global_store_dwordx4 v4, v[52:55], s[48:49]
	s_add_u32 s48, s48, s70
	s_addc_u32 s49, s49, 0
	global_store_dwordx4 v4, v[56:59], s[48:49]
	s_add_u32 s48, s48, s70
	s_addc_u32 s49, s49, 0
	global_store_dwordx4 v4, v[60:63], s[48:49]
	s_add_u32 s33, s33, s56
	s_cmp_lt_u32 s33, 0x7c40
	s_cbranch_scc1 .Lp0_item
